# G1-GEMM bf16 epilogue: rows transposed across lanes (ds_bpermute) so four adjacent lanes write a row's 64 contiguous bytes
# speedup vs baseline: 1.0088x; 1.0088x over previous
; __device__ __forceinline__ unsigned cvt_pk_bf16(float lo, float hi) { unsigned r; asm volatile("v_cvt_pk_bf16_f32 %0, %1, %2" : "=v"(r) : "v"(lo), "v"(hi)); return r; }
;   DI void operator()(const pg8::f32x4 (&acc)[2][2][4][2], const pg8::Unit& u, int wr, int wc, int fr, int fq) const {
;     const int row0 = u.pm * 256 + wr * 64 + fr, col0 = u.pn * 256 + wc * 32 + 8 * fq;
; #pragma unroll
;     for (int ai = 0; ai < 2; ++ai)
; #pragma unroll
;       for (int m = 0; m < 4; ++m) {
;         bfr* rowp = P + (size_t)(row0 + ai * 128 + m * 16) * PW;
; #pragma unroll
;         for (int bj = 0; bj < 2; ++bj) {
;           const int col = col0 + bj * 128;
;           if (col < PW) {
;             pg8::f32x4 v0 = acc[ai][bj][m][0], v1 = acc[ai][bj][m][1];
;             u32x4 w; w.x = pg8::cvt_pk_bf16(v0[0], v0[1]); w.y = pg8::cvt_pk_bf16(v0[2], v0[3]); w.z = pg8::cvt_pk_bf16(v1[0], v1[1]); w.w = pg8::cvt_pk_bf16(v1[2], v1[3]);
;             *(u32x4*)(rowp + col) = w;
;           }
;         }
;       }
;   }
.LBB0_223:
	v_and_b32_e32 v232, 63, v182
	v_lshrrev_b32_e32 v233, 2, v232
	v_and_b32_e32 v234, 3, v232
	v_lshl_add_u32 v235, v234, 4, v233
	v_lshlrev_b32_e32 v235, 2, v235
	v_and_b32_e32 v236, 0xfffffff0, v142
	v_add_u32_e32 v236, v236, v233
	v_lshl_add_u32 v236, s34, 8, v236
	v_and_b32_e32 v237, 0xffffffe0, v144
	v_lshl_add_u32 v237, v234, 3, v237
	v_lshl_or_b32 v237, s31, 8, v237
	s_movk_i32 s4, 0xcc0
	v_cmp_gt_i32_e32 vcc, s4, v237
	v_or_b32_e32 v238, 0x80, v237
	v_cmp_gt_i32_e64 s[4:5], s4, v238
	s_mov_b64 s[18:19], exec
	v_add_u32_e32 v238, 0, v236
	v_mov_b64_e32 v[248:249], s[84:85]
	v_mad_i64_i32 v[248:249], s[98:99], v238, s88, v[248:249]
	v_ashrrev_i32_e32 v251, 31, v237
	v_mov_b32_e32 v250, v237
	v_lshl_add_u64 v[248:249], v[250:251], 1, v[248:249]
	v_cvt_pk_bf16_f32 v240, v124, v125
	v_cvt_pk_bf16_f32 v241, v126, v127
	v_cvt_pk_bf16_f32 v242, v120, v121
	v_cvt_pk_bf16_f32 v243, v122, v123
	ds_bpermute_b32 v244, v235, v240
	ds_bpermute_b32 v245, v235, v241
	ds_bpermute_b32 v246, v235, v242
	ds_bpermute_b32 v247, v235, v243
	s_waitcnt lgkmcnt(0)
	s_and_b64 exec, s[18:19], vcc
	global_store_dwordx4 v[248:249], v[244:247], off
	s_mov_b64 exec, s[18:19]
	v_cvt_pk_bf16_f32 v240, v116, v117
	v_cvt_pk_bf16_f32 v241, v118, v119
	v_cvt_pk_bf16_f32 v242, v108, v109
	v_cvt_pk_bf16_f32 v243, v110, v111
	ds_bpermute_b32 v244, v235, v240
	ds_bpermute_b32 v245, v235, v241
	ds_bpermute_b32 v246, v235, v242
	ds_bpermute_b32 v247, v235, v243
	s_waitcnt lgkmcnt(0)
	s_and_b64 exec, s[18:19], s[4:5]
	global_store_dwordx4 v[248:249], v[244:247], off offset:256
	s_mov_b64 exec, s[18:19]
	v_add_u32_e32 v238, 16, v236
	v_mov_b64_e32 v[248:249], s[84:85]
	v_mad_i64_i32 v[248:249], s[98:99], v238, s88, v[248:249]
	v_ashrrev_i32_e32 v251, 31, v237
	v_mov_b32_e32 v250, v237
	v_lshl_add_u64 v[248:249], v[250:251], 1, v[248:249]
	v_cvt_pk_bf16_f32 v240, v112, v113
	v_cvt_pk_bf16_f32 v241, v114, v115
	v_cvt_pk_bf16_f32 v242, v104, v105
	v_cvt_pk_bf16_f32 v243, v106, v107
	ds_bpermute_b32 v244, v235, v240
	ds_bpermute_b32 v245, v235, v241
	ds_bpermute_b32 v246, v235, v242
	ds_bpermute_b32 v247, v235, v243
	s_waitcnt lgkmcnt(0)
	s_and_b64 exec, s[18:19], vcc
	global_store_dwordx4 v[248:249], v[244:247], off
	s_mov_b64 exec, s[18:19]
	v_cvt_pk_bf16_f32 v240, v100, v101
	v_cvt_pk_bf16_f32 v241, v102, v103
	v_cvt_pk_bf16_f32 v242, v92, v93
	v_cvt_pk_bf16_f32 v243, v94, v95
	ds_bpermute_b32 v244, v235, v240
	ds_bpermute_b32 v245, v235, v241
	ds_bpermute_b32 v246, v235, v242
	ds_bpermute_b32 v247, v235, v243
	s_waitcnt lgkmcnt(0)
	s_and_b64 exec, s[18:19], s[4:5]
	global_store_dwordx4 v[248:249], v[244:247], off offset:256
	s_mov_b64 exec, s[18:19]
	v_add_u32_e32 v238, 32, v236
	v_mov_b64_e32 v[248:249], s[84:85]
	v_mad_i64_i32 v[248:249], s[98:99], v238, s88, v[248:249]
	v_ashrrev_i32_e32 v251, 31, v237
	v_mov_b32_e32 v250, v237
	v_lshl_add_u64 v[248:249], v[250:251], 1, v[248:249]
	v_cvt_pk_bf16_f32 v240, v96, v97
	v_cvt_pk_bf16_f32 v241, v98, v99
	v_cvt_pk_bf16_f32 v242, v88, v89
	v_cvt_pk_bf16_f32 v243, v90, v91
	ds_bpermute_b32 v244, v235, v240
	ds_bpermute_b32 v245, v235, v241
	ds_bpermute_b32 v246, v235, v242
	ds_bpermute_b32 v247, v235, v243
	s_waitcnt lgkmcnt(0)
	s_and_b64 exec, s[18:19], vcc
	global_store_dwordx4 v[248:249], v[244:247], off
	s_mov_b64 exec, s[18:19]
	v_cvt_pk_bf16_f32 v240, v84, v85
	v_cvt_pk_bf16_f32 v241, v86, v87
	v_cvt_pk_bf16_f32 v242, v76, v77
	v_cvt_pk_bf16_f32 v243, v78, v79
	ds_bpermute_b32 v244, v235, v240
	ds_bpermute_b32 v245, v235, v241
	ds_bpermute_b32 v246, v235, v242
	ds_bpermute_b32 v247, v235, v243
	s_waitcnt lgkmcnt(0)
	s_and_b64 exec, s[18:19], s[4:5]
	global_store_dwordx4 v[248:249], v[244:247], off offset:256
	s_mov_b64 exec, s[18:19]
	v_add_u32_e32 v238, 48, v236
	v_mov_b64_e32 v[248:249], s[84:85]
	v_mad_i64_i32 v[248:249], s[98:99], v238, s88, v[248:249]
	v_ashrrev_i32_e32 v251, 31, v237
	v_mov_b32_e32 v250, v237
	v_lshl_add_u64 v[248:249], v[250:251], 1, v[248:249]
	v_cvt_pk_bf16_f32 v240, v80, v81
	v_cvt_pk_bf16_f32 v241, v82, v83
	v_cvt_pk_bf16_f32 v242, v72, v73
	v_cvt_pk_bf16_f32 v243, v74, v75
	ds_bpermute_b32 v244, v235, v240
	ds_bpermute_b32 v245, v235, v241
	ds_bpermute_b32 v246, v235, v242
	ds_bpermute_b32 v247, v235, v243
	s_waitcnt lgkmcnt(0)
	s_and_b64 exec, s[18:19], vcc
	global_store_dwordx4 v[248:249], v[244:247], off
	s_mov_b64 exec, s[18:19]
	v_cvt_pk_bf16_f32 v240, v68, v69
	v_cvt_pk_bf16_f32 v241, v70, v71
	v_cvt_pk_bf16_f32 v242, v64, v65
	v_cvt_pk_bf16_f32 v243, v66, v67
	ds_bpermute_b32 v244, v235, v240
	ds_bpermute_b32 v245, v235, v241
	ds_bpermute_b32 v246, v235, v242
	ds_bpermute_b32 v247, v235, v243
	s_waitcnt lgkmcnt(0)
; __device__ __forceinline__ unsigned cvt_pk_bf16(float lo, float hi) { unsigned r; asm volatile("v_cvt_pk_bf16_f32 %0, %1, %2" : "=v"(r) : "v"(lo), "v"(hi)); return r; }
;   DI void operator()(const pg8::f32x4 (&acc)[2][2][4][2], const pg8::Unit& u, int wr, int wc, int fr, int fq) const {
;     const int row0 = u.pm * 256 + wr * 64 + fr, col0 = u.pn * 256 + wc * 32 + 8 * fq;
; #pragma unroll
;     for (int ai = 0; ai < 2; ++ai)
; #pragma unroll
;       for (int m = 0; m < 4; ++m) {
;         bfr* rowp = P + (size_t)(row0 + ai * 128 + m * 16) * PW;
; #pragma unroll
;         for (int bj = 0; bj < 2; ++bj) {
;           const int col = col0 + bj * 128;
;           if (col < PW) {
;             pg8::f32x4 v0 = acc[ai][bj][m][0], v1 = acc[ai][bj][m][1];
;             u32x4 w; w.x = pg8::cvt_pk_bf16(v0[0], v0[1]); w.y = pg8::cvt_pk_bf16(v0[2], v0[3]); w.z = pg8::cvt_pk_bf16(v1[0], v1[1]); w.w = pg8::cvt_pk_bf16(v1[2], v1[3]);
;             *(u32x4*)(rowp + col) = w;
;           }
;         }
;       }
;   }
	s_and_b64 exec, s[18:19], s[4:5]
	global_store_dwordx4 v[248:249], v[244:247], off offset:256
	s_mov_b64 exec, s[18:19]
	v_add_u32_e32 v238, 128, v236
	v_mov_b64_e32 v[248:249], s[84:85]
	v_mad_i64_i32 v[248:249], s[98:99], v238, s88, v[248:249]
	v_ashrrev_i32_e32 v251, 31, v237
	v_mov_b32_e32 v250, v237
	v_lshl_add_u64 v[248:249], v[250:251], 1, v[248:249]
	v_cvt_pk_bf16_f32 v240, v60, v61
	v_cvt_pk_bf16_f32 v241, v62, v63
	v_cvt_pk_bf16_f32 v242, v56, v57
	v_cvt_pk_bf16_f32 v243, v58, v59
	ds_bpermute_b32 v244, v235, v240
	ds_bpermute_b32 v245, v235, v241
	ds_bpermute_b32 v246, v235, v242
	ds_bpermute_b32 v247, v235, v243
	s_waitcnt lgkmcnt(0)
	s_and_b64 exec, s[18:19], vcc
	global_store_dwordx4 v[248:249], v[244:247], off
	s_mov_b64 exec, s[18:19]
	v_cvt_pk_bf16_f32 v240, v52, v53
	v_cvt_pk_bf16_f32 v241, v54, v55
	v_cvt_pk_bf16_f32 v242, v44, v45
	v_cvt_pk_bf16_f32 v243, v46, v47
	ds_bpermute_b32 v244, v235, v240
	ds_bpermute_b32 v245, v235, v241
	ds_bpermute_b32 v246, v235, v242
	ds_bpermute_b32 v247, v235, v243
	s_waitcnt lgkmcnt(0)
	s_and_b64 exec, s[18:19], s[4:5]
	global_store_dwordx4 v[248:249], v[244:247], off offset:256
	s_mov_b64 exec, s[18:19]
	v_add_u32_e32 v238, 144, v236
	v_mov_b64_e32 v[248:249], s[84:85]
	v_mad_i64_i32 v[248:249], s[98:99], v238, s88, v[248:249]
	v_ashrrev_i32_e32 v251, 31, v237
	v_mov_b32_e32 v250, v237
	v_lshl_add_u64 v[248:249], v[250:251], 1, v[248:249]
	v_cvt_pk_bf16_f32 v240, v48, v49
	v_cvt_pk_bf16_f32 v241, v50, v51
	v_cvt_pk_bf16_f32 v242, v40, v41
	v_cvt_pk_bf16_f32 v243, v42, v43
	ds_bpermute_b32 v244, v235, v240
	ds_bpermute_b32 v245, v235, v241
	ds_bpermute_b32 v246, v235, v242
	ds_bpermute_b32 v247, v235, v243
	s_waitcnt lgkmcnt(0)
	s_and_b64 exec, s[18:19], vcc
	global_store_dwordx4 v[248:249], v[244:247], off
	s_mov_b64 exec, s[18:19]
	v_cvt_pk_bf16_f32 v240, v36, v37
	v_cvt_pk_bf16_f32 v241, v38, v39
	v_cvt_pk_bf16_f32 v242, v28, v29
	v_cvt_pk_bf16_f32 v243, v30, v31
	ds_bpermute_b32 v244, v235, v240
	ds_bpermute_b32 v245, v235, v241
	ds_bpermute_b32 v246, v235, v242
	ds_bpermute_b32 v247, v235, v243
	s_waitcnt lgkmcnt(0)
	s_and_b64 exec, s[18:19], s[4:5]
	global_store_dwordx4 v[248:249], v[244:247], off offset:256
	s_mov_b64 exec, s[18:19]
	v_add_u32_e32 v238, 160, v236
	v_mov_b64_e32 v[248:249], s[84:85]
	v_mad_i64_i32 v[248:249], s[98:99], v238, s88, v[248:249]
	v_ashrrev_i32_e32 v251, 31, v237
	v_mov_b32_e32 v250, v237
	v_lshl_add_u64 v[248:249], v[250:251], 1, v[248:249]
	v_cvt_pk_bf16_f32 v240, v32, v33
	v_cvt_pk_bf16_f32 v241, v34, v35
	v_cvt_pk_bf16_f32 v242, v24, v25
	v_cvt_pk_bf16_f32 v243, v26, v27
	ds_bpermute_b32 v244, v235, v240
	ds_bpermute_b32 v245, v235, v241
	ds_bpermute_b32 v246, v235, v242
	ds_bpermute_b32 v247, v235, v243
	s_waitcnt lgkmcnt(0)
	s_and_b64 exec, s[18:19], vcc
	global_store_dwordx4 v[248:249], v[244:247], off
	s_mov_b64 exec, s[18:19]
	v_cvt_pk_bf16_f32 v240, v20, v21
	v_cvt_pk_bf16_f32 v241, v22, v23
	v_cvt_pk_bf16_f32 v242, v12, v13
	v_cvt_pk_bf16_f32 v243, v14, v15
	ds_bpermute_b32 v244, v235, v240
	ds_bpermute_b32 v245, v235, v241
	ds_bpermute_b32 v246, v235, v242
	ds_bpermute_b32 v247, v235, v243
	s_waitcnt lgkmcnt(0)
	s_and_b64 exec, s[18:19], s[4:5]
	global_store_dwordx4 v[248:249], v[244:247], off offset:256
	s_mov_b64 exec, s[18:19]
	v_add_u32_e32 v238, 176, v236
	v_mov_b64_e32 v[248:249], s[84:85]
	v_mad_i64_i32 v[248:249], s[98:99], v238, s88, v[248:249]
	v_ashrrev_i32_e32 v251, 31, v237
	v_mov_b32_e32 v250, v237
	v_lshl_add_u64 v[248:249], v[250:251], 1, v[248:249]
	v_cvt_pk_bf16_f32 v240, v16, v17
	v_cvt_pk_bf16_f32 v241, v18, v19
	v_cvt_pk_bf16_f32 v242, v8, v9
	v_cvt_pk_bf16_f32 v243, v10, v11
	ds_bpermute_b32 v244, v235, v240
	ds_bpermute_b32 v245, v235, v241
	ds_bpermute_b32 v246, v235, v242
	ds_bpermute_b32 v247, v235, v243
	s_waitcnt lgkmcnt(0)
	s_and_b64 exec, s[18:19], vcc
	global_store_dwordx4 v[248:249], v[244:247], off
	s_mov_b64 exec, s[18:19]
	v_cvt_pk_bf16_f32 v240, v4, v5
	v_cvt_pk_bf16_f32 v241, v6, v7
	v_cvt_pk_bf16_f32 v242, v0, v1
	v_cvt_pk_bf16_f32 v243, v2, v3
	ds_bpermute_b32 v244, v235, v240
	ds_bpermute_b32 v245, v235, v241
	ds_bpermute_b32 v246, v235, v242
	ds_bpermute_b32 v247, v235, v243
	s_waitcnt lgkmcnt(0)
	s_and_b64 exec, s[18:19], s[4:5]
	global_store_dwordx4 v[248:249], v[244:247], off offset:256
	s_mov_b64 exec, s[18:19]
	s_andn2_b64 vcc, exec, s[2:3]
	s_mov_b64 s[2:3], -1
	s_cbranch_vccnz .LBB0_216
